# A loop drain now ends with lgkmcnt(0)+barrier so no wave starts the epilogue LDS staging while another still reads V (race fix)
# speedup vs baseline: 1.0038x; 1.0038x over previous
; #define SBAR() __builtin_amdgcn_sched_barrier(0)
; DEV void attn_a_item(const Params& P, int layer, int batch, int item, char* lds) {
;     ...
;     trq<0, 0>(vb, fa);
; #pragma unroll
;     for (int ks = 0; ks < 4; ++ks) p1 = __builtin_amdgcn_mfma_f32_32x32x16_bf16(kf[2 * ks + 1], qr[ks], p1, 0, 0, 0);
;     sm_exp(p0, lsum); sm_pack(p0, pa0, pa1);
;     asm volatile("s_waitcnt lgkmcnt(0)" ::: "memory"); SBAR();
;     trq<0, 2>(vb, fb);
;     mmaq(o[0], o[1], fa, pa0, pa1);
;     sm_exp(p1, lsum);
;     asm volatile("s_waitcnt lgkmcnt(0)" ::: "memory"); SBAR();
;     trq<2, 0>(vb, fa);
;     mmaq(o[2], o[3], fb, pa0, pa1);
;     sm_pack(p1, pa2, pa3);
;     asm volatile("s_waitcnt lgkmcnt(0)" ::: "memory"); SBAR();
;     trq<2, 2>(vb, fb);
;     mmaq(o[0], o[1], fa, pa2, pa3);
;     asm volatile("s_waitcnt lgkmcnt(0)" ::: "memory"); SBAR();
;     mmaq(o[2], o[3], fb, pa2, pa3);
;     asm volatile("s_waitcnt vmcnt(0)" ::: "memory");
;     __syncthreads();
;   }
;     ...
;   lsum = swapsum(lsum);
;   if (hi == 0) wsl[r32] = (c ? lam : 1.f) / lsum;
.Ldfa_drain1:
	ds_read_b64_tr_b16 v[218:219], v173 offset:16384
	ds_read_b64_tr_b16 v[220:221], v173 offset:18432
	ds_read_b64_tr_b16 v[222:223], v173 offset:16896
	ds_read_b64_tr_b16 v[224:225], v173 offset:18944
	ds_read_b64_tr_b16 v[232:233], v173 offset:17408
	ds_read_b64_tr_b16 v[234:235], v173 offset:19456
	ds_read_b64_tr_b16 v[236:237], v173 offset:17920
	ds_read_b64_tr_b16 v[238:239], v173 offset:19968
	ds_read_b64_tr_b16 v[240:241], v173 offset:20480
	ds_read_b64_tr_b16 v[242:243], v173 offset:22528
	ds_read_b64_tr_b16 v[244:245], v173 offset:20992
	ds_read_b64_tr_b16 v[246:247], v173 offset:23040
	ds_read_b64_tr_b16 v[248:249], v173 offset:21504
	ds_read_b64_tr_b16 v[250:251], v173 offset:23552
	ds_read_b64_tr_b16 v[194:195], v173 offset:22016
	ds_read_b64_tr_b16 v[196:197], v173 offset:24064
	v_mfma_f32_32x32x16_bf16 v[48:63], v[150:153], v[202:205], v[48:63]
	ds_read_b64_tr_b16 v[202:203], v173 offset:24576
	ds_read_b64_tr_b16 v[204:205], v173 offset:26624
	v_mfma_f32_32x32x16_bf16 v[32:47], v[150:153], v[206:209], v[32:47]
	ds_read_b64_tr_b16 v[206:207], v173 offset:25088
	ds_read_b64_tr_b16 v[208:209], v173 offset:27136
	v_mfma_f32_32x32x16_bf16 v[16:31], v[150:153], v[210:213], v[16:31]
	ds_read_b64_tr_b16 v[210:211], v173 offset:25600
	ds_read_b64_tr_b16 v[212:213], v173 offset:27648
	v_mfma_f32_32x32x16_bf16 v[0:15], v[150:153], v[214:217], v[0:15]
	ds_read_b64_tr_b16 v[214:215], v173 offset:26112
	ds_read_b64_tr_b16 v[216:217], v173 offset:28160
	s_waitcnt lgkmcnt(14)
	v_mfma_f32_32x32x16_bf16 v[48:63], v[176:179], v[218:221], v[48:63]
	ds_read_b64_tr_b16 v[218:219], v173 offset:28672
	ds_read_b64_tr_b16 v[220:221], v173 offset:30720
	s_waitcnt lgkmcnt(14)
	v_mfma_f32_32x32x16_bf16 v[32:47], v[176:179], v[222:225], v[32:47]
	ds_read_b64_tr_b16 v[222:223], v173 offset:29184
	ds_read_b64_tr_b16 v[224:225], v173 offset:31232
	s_waitcnt lgkmcnt(14)
	v_mfma_f32_32x32x16_bf16 v[16:31], v[176:179], v[232:235], v[16:31]
	ds_read_b64_tr_b16 v[232:233], v173 offset:29696
	ds_read_b64_tr_b16 v[234:235], v173 offset:31744
	s_waitcnt lgkmcnt(14)
	v_mfma_f32_32x32x16_bf16 v[0:15], v[176:179], v[236:239], v[0:15]
	ds_read_b64_tr_b16 v[236:237], v173 offset:30208
	ds_read_b64_tr_b16 v[238:239], v173 offset:32256
	s_waitcnt lgkmcnt(14)
	v_mfma_f32_32x32x16_bf16 v[48:63], v[180:183], v[240:243], v[48:63]
	s_waitcnt lgkmcnt(14)
	v_mfma_f32_32x32x16_bf16 v[32:47], v[180:183], v[244:247], v[32:47]
	s_waitcnt lgkmcnt(14)
	v_mfma_f32_32x32x16_bf16 v[16:31], v[180:183], v[248:251], v[16:31]
	s_waitcnt lgkmcnt(14)
	v_mfma_f32_32x32x16_bf16 v[0:15], v[180:183], v[194:197], v[0:15]
	s_waitcnt lgkmcnt(14)
	v_mfma_f32_32x32x16_bf16 v[48:63], v[198:201], v[202:205], v[48:63]
	s_waitcnt lgkmcnt(12)
	v_mfma_f32_32x32x16_bf16 v[32:47], v[198:201], v[206:209], v[32:47]
	s_waitcnt lgkmcnt(10)
	v_mfma_f32_32x32x16_bf16 v[16:31], v[198:201], v[210:213], v[16:31]
	s_waitcnt lgkmcnt(8)
	v_mfma_f32_32x32x16_bf16 v[0:15], v[198:201], v[214:217], v[0:15]
	s_waitcnt lgkmcnt(6)
	v_mfma_f32_32x32x16_bf16 v[48:63], v[154:157], v[218:221], v[48:63]
	s_waitcnt lgkmcnt(4)
	v_mfma_f32_32x32x16_bf16 v[32:47], v[154:157], v[222:225], v[32:47]
	s_waitcnt lgkmcnt(2)
	v_mfma_f32_32x32x16_bf16 v[16:31], v[154:157], v[232:235], v[16:31]
	s_waitcnt lgkmcnt(0)
	v_mfma_f32_32x32x16_bf16 v[0:15], v[154:157], v[236:239], v[0:15]
	v_add_f32_e32 v167, v167, v80
	v_add_f32_e32 v167, v167, v81
	v_add_f32_e32 v167, v167, v82
	v_add_f32_e32 v167, v167, v83
	v_add_f32_e32 v167, v167, v84
	v_add_f32_e32 v167, v167, v85
	v_add_f32_e32 v167, v167, v86
	v_add_f32_e32 v167, v167, v87
	v_add_f32_e32 v167, v167, v88
	v_add_f32_e32 v167, v167, v89
	v_add_f32_e32 v167, v167, v90
	v_add_f32_e32 v167, v167, v91
	v_add_f32_e32 v167, v167, v92
	v_add_f32_e32 v167, v167, v93
	v_add_f32_e32 v167, v167, v94
	v_add_f32_e32 v167, v167, v95
	s_waitcnt lgkmcnt(0)
	s_barrier
	s_branch .LBB0_383
; #define SBAR() __builtin_amdgcn_sched_barrier(0)
; DEV void attn_a_item(const Params& P, int layer, int batch, int item, char* lds) {
;     ...
;     trq<0, 0>(vb, fa);
; #pragma unroll
;     for (int ks = 0; ks < 4; ++ks) p1 = __builtin_amdgcn_mfma_f32_32x32x16_bf16(kf[2 * ks + 1], qr[ks], p1, 0, 0, 0);
;     sm_exp(p0, lsum); sm_pack(p0, pa0, pa1);
;     asm volatile("s_waitcnt lgkmcnt(0)" ::: "memory"); SBAR();
;     trq<0, 2>(vb, fb);
;     mmaq(o[0], o[1], fa, pa0, pa1);
;     sm_exp(p1, lsum);
;     asm volatile("s_waitcnt lgkmcnt(0)" ::: "memory"); SBAR();
;     trq<2, 0>(vb, fa);
;     mmaq(o[2], o[3], fb, pa0, pa1);
;     sm_pack(p1, pa2, pa3);
;     asm volatile("s_waitcnt lgkmcnt(0)" ::: "memory"); SBAR();
;     trq<2, 2>(vb, fb);
;     mmaq(o[0], o[1], fa, pa2, pa3);
;     asm volatile("s_waitcnt lgkmcnt(0)" ::: "memory"); SBAR();
;     mmaq(o[2], o[3], fb, pa2, pa3);
;     asm volatile("s_waitcnt vmcnt(0)" ::: "memory");
;     __syncthreads();
;   }
;     ...
;   lsum = swapsum(lsum);
;   if (hi == 0) wsl[r32] = (c ? lam : 1.f) / lsum;
.Ldfa_drain0_pre:
.Ldfa_drain0:
	ds_read_b64_tr_b16 v[218:219], v173 offset:0
	ds_read_b64_tr_b16 v[220:221], v173 offset:2048
	ds_read_b64_tr_b16 v[222:223], v173 offset:512
	ds_read_b64_tr_b16 v[224:225], v173 offset:2560
	ds_read_b64_tr_b16 v[232:233], v173 offset:1024
	ds_read_b64_tr_b16 v[234:235], v173 offset:3072
	ds_read_b64_tr_b16 v[236:237], v173 offset:1536
	ds_read_b64_tr_b16 v[238:239], v173 offset:3584
	ds_read_b64_tr_b16 v[240:241], v173 offset:4096
	ds_read_b64_tr_b16 v[242:243], v173 offset:6144
	ds_read_b64_tr_b16 v[244:245], v173 offset:4608
	ds_read_b64_tr_b16 v[246:247], v173 offset:6656
	ds_read_b64_tr_b16 v[248:249], v173 offset:5120
	ds_read_b64_tr_b16 v[250:251], v173 offset:7168
	ds_read_b64_tr_b16 v[194:195], v173 offset:5632
	ds_read_b64_tr_b16 v[196:197], v173 offset:7680
	v_mfma_f32_32x32x16_bf16 v[48:63], v[154:157], v[202:205], v[48:63]
	ds_read_b64_tr_b16 v[202:203], v173 offset:8192
	ds_read_b64_tr_b16 v[204:205], v173 offset:10240
	v_mfma_f32_32x32x16_bf16 v[32:47], v[154:157], v[206:209], v[32:47]
	ds_read_b64_tr_b16 v[206:207], v173 offset:8704
	ds_read_b64_tr_b16 v[208:209], v173 offset:10752
	v_mfma_f32_32x32x16_bf16 v[16:31], v[154:157], v[210:213], v[16:31]
	ds_read_b64_tr_b16 v[210:211], v173 offset:9216
	ds_read_b64_tr_b16 v[212:213], v173 offset:11264
	v_mfma_f32_32x32x16_bf16 v[0:15], v[154:157], v[214:217], v[0:15]
	ds_read_b64_tr_b16 v[214:215], v173 offset:9728
	ds_read_b64_tr_b16 v[216:217], v173 offset:11776
	s_waitcnt lgkmcnt(14)
	v_mfma_f32_32x32x16_bf16 v[48:63], v[176:179], v[218:221], v[48:63]
	ds_read_b64_tr_b16 v[218:219], v173 offset:12288
	ds_read_b64_tr_b16 v[220:221], v173 offset:14336
	s_waitcnt lgkmcnt(14)
	v_mfma_f32_32x32x16_bf16 v[32:47], v[176:179], v[222:225], v[32:47]
	ds_read_b64_tr_b16 v[222:223], v173 offset:12800
	ds_read_b64_tr_b16 v[224:225], v173 offset:14848
	s_waitcnt lgkmcnt(14)
	v_mfma_f32_32x32x16_bf16 v[16:31], v[176:179], v[232:235], v[16:31]
	ds_read_b64_tr_b16 v[232:233], v173 offset:13312
	ds_read_b64_tr_b16 v[234:235], v173 offset:15360
	s_waitcnt lgkmcnt(14)
	v_mfma_f32_32x32x16_bf16 v[0:15], v[176:179], v[236:239], v[0:15]
	ds_read_b64_tr_b16 v[236:237], v173 offset:13824
	ds_read_b64_tr_b16 v[238:239], v173 offset:15872
	s_waitcnt lgkmcnt(14)
	v_mfma_f32_32x32x16_bf16 v[48:63], v[180:183], v[240:243], v[48:63]
	s_waitcnt lgkmcnt(14)
	v_mfma_f32_32x32x16_bf16 v[32:47], v[180:183], v[244:247], v[32:47]
	s_waitcnt lgkmcnt(14)
	v_mfma_f32_32x32x16_bf16 v[16:31], v[180:183], v[248:251], v[16:31]
	s_waitcnt lgkmcnt(14)
	v_mfma_f32_32x32x16_bf16 v[0:15], v[180:183], v[194:197], v[0:15]
	s_waitcnt lgkmcnt(14)
	v_mfma_f32_32x32x16_bf16 v[48:63], v[186:189], v[202:205], v[48:63]
	s_waitcnt lgkmcnt(12)
	v_mfma_f32_32x32x16_bf16 v[32:47], v[186:189], v[206:209], v[32:47]
	s_waitcnt lgkmcnt(10)
	v_mfma_f32_32x32x16_bf16 v[16:31], v[186:189], v[210:213], v[16:31]
	s_waitcnt lgkmcnt(8)
	v_mfma_f32_32x32x16_bf16 v[0:15], v[186:189], v[214:217], v[0:15]
	s_waitcnt lgkmcnt(6)
	v_mfma_f32_32x32x16_bf16 v[48:63], v[150:153], v[218:221], v[48:63]
	s_waitcnt lgkmcnt(4)
	v_mfma_f32_32x32x16_bf16 v[32:47], v[150:153], v[222:225], v[32:47]
	s_waitcnt lgkmcnt(2)
	v_mfma_f32_32x32x16_bf16 v[16:31], v[150:153], v[232:235], v[16:31]
	s_waitcnt lgkmcnt(0)
	v_mfma_f32_32x32x16_bf16 v[0:15], v[150:153], v[236:239], v[0:15]
	v_add_f32_e32 v167, v167, v80
	v_add_f32_e32 v167, v167, v81
	v_add_f32_e32 v167, v167, v82
	v_add_f32_e32 v167, v167, v83
	v_add_f32_e32 v167, v167, v84
	v_add_f32_e32 v167, v167, v85
	v_add_f32_e32 v167, v167, v86
	v_add_f32_e32 v167, v167, v87
	v_add_f32_e32 v167, v167, v88
	v_add_f32_e32 v167, v167, v89
	v_add_f32_e32 v167, v167, v90
	v_add_f32_e32 v167, v167, v91
	v_add_f32_e32 v167, v167, v92
	v_add_f32_e32 v167, v167, v93
	v_add_f32_e32 v167, v167, v94
	v_add_f32_e32 v167, v167, v95
	s_waitcnt lgkmcnt(0)
	s_barrier
	s_branch .LBB0_383
